# on top of best: swiglu epilogue deferred into the next unit's first K-iteration
# speedup vs baseline: 1.0079x; 1.0079x over previous
; #define PG8_STAGE(bufoff, gbase, voff) do { _Pragma("unroll") for (int _i = 0; _i < 2; ++_i) \
;         __builtin_amdgcn_global_load_lds((const unsigned*)((const char*)(gbase) + (voff)[_i]), (PG8_LAS unsigned*)(lds + (bufoff) + ldsw + _i * 8192), 16, 0, 0); } while (0)
; #define PG8_LDA(dst, b, h) do { _Pragma("unroll") for (int m = 0; m < 4; ++m) _Pragma("unroll") for (int k = 0; k < 2; ++k) dst[m][k] = *(const PG8_LAS bf16x8*)(lds + PG8_SA(b, h) + aoff + m * 2048 + k * 1024); } while (0)
; #define PG8_LDB(dst, b, h) do { _Pragma("unroll") for (int n = 0; n < 2; ++n) _Pragma("unroll") for (int k = 0; k < 2; ++k) dst[n][k] = *(const PG8_LAS bf16x8*)(lds + PG8_SB(b, h) + boff + n * 2048 + k * 1024); } while (0)
; #define PG8_WAIT_V(n) asm volatile("s_waitcnt vmcnt(" #n ")" ::: "memory")
; #define PG8_BAR __builtin_amdgcn_s_barrier()
;     __device__ __forceinline__ void operator()(const f32x4 (&acc)[2][2][4][2], const Unit& u, int wr, int wc, int fr, int fq, PG8_LAS unsigned char* lds, int& rs_pm, int& rs_tog) const {
;     ...
;                 const int row = row0 + ai * HALF + m * 16;
;                 const float rr = rt_[ai * HALF + m * 16], k1 = -kLog2e * rr, rr2 = rr * rr;
;                 const f32x4 a0 = acc[ai][0][m][0], a1 = acc[ai][0][m][1];
;                 f32x4 e0 = a0 * k1, e1 = a1 * k1;
;                 f32x4 g0 = (a0 * acc[ai][1][m][0]) * rr2, g1 = (a1 * acc[ai][1][m][1]) * rr2;
; #pragma unroll
;                 for (int i = 0; i < 4; ++i) { e0[i] = __builtin_amdgcn_exp2f(e0[i]); e1[i] = __builtin_amdgcn_exp2f(e1[i]); }
;                 e0 = e0 + 1.0f; e1 = e1 + 1.0f;
; #pragma unroll
;                 for (int i = 0; i < 4; ++i) { e0[i] = __builtin_amdgcn_rcpf(e0[i]); e1[i] = __builtin_amdgcn_rcpf(e1[i]); }
;                 g0 = g0 * e0; g1 = g1 * e1;
; template <class Epi, class Sched, bool ALIGN_EPI = false, bool SP2 = false>
; __device__ __forceinline__ void gemm_phase(PG8_LAS unsigned char* lds, const Gemm g, const Sched& S, const Epi& E) {
;     ...
;             PG8_LDB(B0, 0, 0); PG8_LDB(B1, 0, 1); PG8_SCHED; PG8_LDA(At, 0, 0); PG8_STAGE(PG8_SA(1, 1), a1 + hstep, voffA);
;             PG8_WAIT_V(8); PG8_WAIT_L(0); PG8_BAR; PG8_MMA(0, 0, At, B0); PG8_MMA(0, 1, At, B1); PG8_BAR; PG8_SCHED;
;             PG8_LDA(At, 0, 1); PG8_STAGE(PG8_SB(0, 0), b2, voffB); PG8_STAGE(PG8_SB(0, 1), b2 + hstep, voffB); PG8_STAGE(PG8_SA(0, 0), a2, voffA);
.Ldef_sp1_join:
	s_waitcnt lgkmcnt(0)
	s_barrier
	s_setprio 1
	v_mfma_f32_16x16x32_bf16 v[114:117], v[146:149], v[178:181], v[114:117]
	v_mfma_f32_16x16x32_bf16 v[114:117], v[150:153], v[182:185], v[114:117]
	v_mfma_f32_16x16x32_bf16 v[98:101], v[146:149], v[186:189], v[98:101]
	v_mfma_f32_16x16x32_bf16 v[98:101], v[150:153], v[190:193], v[98:101]
	v_mfma_f32_16x16x32_bf16 v[82:85], v[146:149], v[202:205], v[82:85]
	v_mfma_f32_16x16x32_bf16 v[82:85], v[150:153], v[206:209], v[82:85]
	v_mfma_f32_16x16x32_bf16 v[66:69], v[146:149], v[210:213], v[66:69]
	v_mfma_f32_16x16x32_bf16 v[66:69], v[150:153], v[214:217], v[66:69]
	v_mfma_f32_16x16x32_bf16 v[118:121], v[154:157], v[178:181], v[118:121]
	v_mfma_f32_16x16x32_bf16 v[118:121], v[158:161], v[182:185], v[118:121]
	v_mfma_f32_16x16x32_bf16 v[102:105], v[154:157], v[186:189], v[102:105]
	v_mfma_f32_16x16x32_bf16 v[102:105], v[158:161], v[190:193], v[102:105]
	v_mfma_f32_16x16x32_bf16 v[86:89], v[154:157], v[202:205], v[86:89]
	v_mfma_f32_16x16x32_bf16 v[86:89], v[158:161], v[206:209], v[86:89]
	v_mfma_f32_16x16x32_bf16 v[70:73], v[154:157], v[210:213], v[70:73]
	v_mfma_f32_16x16x32_bf16 v[70:73], v[158:161], v[214:217], v[70:73]
	v_mfma_f32_16x16x32_bf16 v[122:125], v[162:165], v[178:181], v[122:125]
	v_mfma_f32_16x16x32_bf16 v[122:125], v[166:169], v[182:185], v[122:125]
	v_mfma_f32_16x16x32_bf16 v[106:109], v[162:165], v[186:189], v[106:109]
	v_mfma_f32_16x16x32_bf16 v[106:109], v[166:169], v[190:193], v[106:109]
	v_mfma_f32_16x16x32_bf16 v[90:93], v[162:165], v[202:205], v[90:93]
	v_mfma_f32_16x16x32_bf16 v[90:93], v[166:169], v[206:209], v[90:93]
	v_mfma_f32_16x16x32_bf16 v[74:77], v[162:165], v[210:213], v[74:77]
	v_mfma_f32_16x16x32_bf16 v[74:77], v[166:169], v[214:217], v[74:77]
	v_mfma_f32_16x16x32_bf16 v[126:129], v[170:173], v[178:181], v[126:129]
	v_mfma_f32_16x16x32_bf16 v[126:129], v[174:177], v[182:185], v[126:129]
	v_mfma_f32_16x16x32_bf16 v[110:113], v[170:173], v[186:189], v[110:113]
	v_mfma_f32_16x16x32_bf16 v[110:113], v[174:177], v[190:193], v[110:113]
	v_mfma_f32_16x16x32_bf16 v[94:97], v[170:173], v[202:205], v[94:97]
	v_mfma_f32_16x16x32_bf16 v[94:97], v[174:177], v[206:209], v[94:97]
	v_mfma_f32_16x16x32_bf16 v[78:81], v[170:173], v[210:213], v[78:81]
	v_mfma_f32_16x16x32_bf16 v[78:81], v[174:177], v[214:217], v[78:81]
	s_setprio 0
	s_barrier
	s_add_i32 s38, s39, s27
	v_lshl_add_u64 v[194:195], s[56:57], 0, v[0:1]
	s_mov_b32 m0, s38
	ds_read_b128 v[178:181], v144 offset:16384
	ds_read_b128 v[182:185], v144 offset:17408
	ds_read_b128 v[186:189], v144 offset:18432
	ds_read_b128 v[190:193], v144 offset:19456
	ds_read_b128 v[202:205], v144 offset:20480
	ds_read_b128 v[206:209], v144 offset:21504
	ds_read_b128 v[210:213], v144 offset:22528
	ds_read_b128 v[214:217], v144 offset:23552
	global_load_lds_dwordx4 v[194:195], off
	s_add_i32 m0, s38, 0x2000
	s_add_u32 s38, s56, 0x40000
	v_lshl_add_u64 v[218:219], s[56:57], 0, v[130:131]
	s_addc_u32 s39, s57, 0
	s_add_i32 s18, s18, s27
	global_load_lds_dwordx4 v[218:219], off
	v_lshl_add_u64 v[220:221], s[38:39], 0, v[0:1]
	s_mov_b32 m0, s18
	v_lshl_add_u64 v[222:223], s[64:65], 0, v[132:133]
	global_load_lds_dwordx4 v[220:221], off
	v_lshl_add_u64 v[220:221], s[38:39], 0, v[130:131]
	s_add_i32 m0, s18, 0x2000
	s_nop 0
	global_load_lds_dwordx4 v[220:221], off
	v_lshl_add_u64 v[220:221], s[64:65], 0, v[134:135]
	s_mov_b32 m0, s29
	s_nop 0
	global_load_lds_dwordx4 v[220:221], off
	s_mov_b32 m0, s33
	s_nop 0
	global_load_lds_dwordx4 v[222:223], off
	s_cmp_eq_u32 s101, 0
	s_cbranch_scc1 .Ldef_sp2_skip
	v_lshl_add_u32 v226, s73, 10, v142
	ds_read_b32 v227, v226 offset:512
	ds_read_b32 v199, v226 offset:576
	ds_read_b32 v200, v226 offset:640
	ds_read_b32 v201, v226 offset:704
	s_lshl_b32 vcc_lo, s77, 8
	s_addk_i32 vcc_lo, 0x80
	s_mul_i32 vcc_lo, vcc_lo, s86
	s_lshl_b32 vcc_hi, s100, 8
	s_add_i32 vcc_lo, vcc_lo, vcc_hi
	v_mul_u32_u24_e32 v198, 0x1600, v140
	v_lshl_add_u32 v198, v143, 1, v198
	v_add_u32_e32 v198, vcc_lo, v198
	s_waitcnt lgkmcnt(0)
	v_mul_f32_e32 v226, 0xbfb8aa3b, v227
	v_mul_f32_e32 v228, v227, v227
	v_pk_mul_f32 v[58:59], v[50:51], v[58:59]
	v_pk_mul_f32 v[60:61], v[52:53], v[60:61]
	v_pk_mul_f32 v[62:63], v[54:55], v[62:63]
	v_pk_mul_f32 v[64:65], v[56:57], v[64:65]
	v_pk_mul_f32 v[50:51], v[50:51], v[226:227] op_sel_hi:[1,0]
	v_pk_mul_f32 v[52:53], v[52:53], v[226:227] op_sel_hi:[1,0]
	v_pk_mul_f32 v[54:55], v[54:55], v[226:227] op_sel_hi:[1,0]
	v_pk_mul_f32 v[56:57], v[56:57], v[226:227] op_sel_hi:[1,0]
	v_exp_f32_e32 v50, v50
	v_exp_f32_e32 v51, v51
	v_exp_f32_e32 v52, v52
	v_exp_f32_e32 v53, v53
	v_exp_f32_e32 v54, v54
	v_exp_f32_e32 v55, v55
	v_exp_f32_e32 v56, v56
	v_exp_f32_e32 v57, v57
	v_pk_add_f32 v[50:51], v[50:51], 1.0 op_sel_hi:[1,0]
	v_pk_add_f32 v[52:53], v[52:53], 1.0 op_sel_hi:[1,0]
	v_pk_add_f32 v[54:55], v[54:55], 1.0 op_sel_hi:[1,0]
	v_pk_add_f32 v[56:57], v[56:57], 1.0 op_sel_hi:[1,0]
	v_rcp_f32_e32 v50, v50
	v_rcp_f32_e32 v51, v51
	v_rcp_f32_e32 v52, v52
	v_rcp_f32_e32 v53, v53
	v_rcp_f32_e32 v54, v54
	v_rcp_f32_e32 v55, v55
	v_rcp_f32_e32 v56, v56
	v_rcp_f32_e32 v57, v57
	v_pk_mul_f32 v[58:59], v[58:59], v[228:229] op_sel_hi:[1,0]
	v_pk_mul_f32 v[60:61], v[60:61], v[228:229] op_sel_hi:[1,0]
	v_pk_mul_f32 v[62:63], v[62:63], v[228:229] op_sel_hi:[1,0]
	v_pk_mul_f32 v[64:65], v[64:65], v[228:229] op_sel_hi:[1,0]
	v_pk_mul_f32 v[58:59], v[58:59], v[50:51]
	v_pk_mul_f32 v[60:61], v[60:61], v[52:53]
	v_pk_mul_f32 v[62:63], v[62:63], v[54:55]
	v_pk_mul_f32 v[64:65], v[64:65], v[56:57]
	v_cvt_pk_bf16_f32 v50, v58, v59
	v_cvt_pk_bf16_f32 v51, v60, v61
	v_cvt_pk_bf16_f32 v52, v62, v63
	v_cvt_pk_bf16_f32 v53, v64, v65
; __device__ __forceinline__ unsigned cvt_pk_bf16(float lo, float hi) { unsigned r; asm volatile("v_cvt_pk_bf16_f32 %0, %1, %2" : "=v"(r) : "v"(lo), "v"(hi)); return r; }
;     __device__ __forceinline__ void operator()(const f32x4 (&acc)[2][2][4][2], const Unit& u, int wr, int wc, int fr, int fq, PG8_LAS unsigned char* lds, int& rs_pm, int& rs_tog) const {
;     ...
;                 const int row = row0 + ai * HALF + m * 16;
;                 const float rr = rt_[ai * HALF + m * 16], k1 = -kLog2e * rr, rr2 = rr * rr;
;                 const f32x4 a0 = acc[ai][0][m][0], a1 = acc[ai][0][m][1];
;                 f32x4 e0 = a0 * k1, e1 = a1 * k1;
;                 f32x4 g0 = (a0 * acc[ai][1][m][0]) * rr2, g1 = (a1 * acc[ai][1][m][1]) * rr2;
; #pragma unroll
;                 for (int i = 0; i < 4; ++i) { e0[i] = __builtin_amdgcn_exp2f(e0[i]); e1[i] = __builtin_amdgcn_exp2f(e1[i]); }
;                 e0 = e0 + 1.0f; e1 = e1 + 1.0f;
; #pragma unroll
;                 for (int i = 0; i < 4; ++i) { e0[i] = __builtin_amdgcn_rcpf(e0[i]); e1[i] = __builtin_amdgcn_rcpf(e1[i]); }
;                 g0 = g0 * e0; g1 = g1 * e1;
;                 const float b[8] = {g0[0], g0[1], g0[2], g0[3], g1[0], g1[1], g1[2], g1[3]};
;                 u32x4 w; w.x = cvt_pk_bf16(b[0], b[1]); w.y = cvt_pk_bf16(b[2], b[3]); w.z = cvt_pk_bf16(b[4], b[5]); w.w = cvt_pk_bf16(b[6], b[7]);
;                 *(u32x4*)(act + (size_t)row * ldc + col0) = w;
; template <class Epi, class Sched, bool ALIGN_EPI = false, bool SP2 = false>
; __device__ __forceinline__ void gemm_phase(PG8_LAS unsigned char* lds, const Gemm g, const Sched& S, const Epi& E) {
;     ...
; #pragma unroll
;         for (int a = 0; a < 2; ++a)
; #pragma unroll
;             for (int b = 0; b < 2; ++b)
; #pragma unroll
;                 for (int m = 0; m < 4; ++m)
; #pragma unroll
;                     for (int n = 0; n < 2; ++n) { unsigned long long lo_, hi_; asm volatile("v_mov_b64 %0, 0\n\tv_mov_b64 %1, 0" : "=v"(lo_), "=v"(hi_)); acc[a][b][m][n] = __builtin_bit_cast(f32x4, (u64x2_t){lo_, hi_}); }
	global_store_dwordx4 v198, v[50:53], s[10:11]
	v_add_u32_e32 v198, 0x16000, v198
	v_mul_f32_e32 v226, 0xbfb8aa3b, v199
	v_mul_f32_e32 v228, v199, v199
	v_pk_mul_f32 v[42:43], v[34:35], v[42:43]
	v_pk_mul_f32 v[44:45], v[36:37], v[44:45]
	v_pk_mul_f32 v[46:47], v[38:39], v[46:47]
	v_pk_mul_f32 v[48:49], v[40:41], v[48:49]
	v_pk_mul_f32 v[34:35], v[34:35], v[226:227] op_sel_hi:[1,0]
	v_pk_mul_f32 v[36:37], v[36:37], v[226:227] op_sel_hi:[1,0]
	v_pk_mul_f32 v[38:39], v[38:39], v[226:227] op_sel_hi:[1,0]
	v_pk_mul_f32 v[40:41], v[40:41], v[226:227] op_sel_hi:[1,0]
	v_exp_f32_e32 v34, v34
	v_exp_f32_e32 v35, v35
	v_exp_f32_e32 v36, v36
	v_exp_f32_e32 v37, v37
	v_exp_f32_e32 v38, v38
	v_exp_f32_e32 v39, v39
	v_exp_f32_e32 v40, v40
	v_exp_f32_e32 v41, v41
	v_pk_add_f32 v[34:35], v[34:35], 1.0 op_sel_hi:[1,0]
	v_pk_add_f32 v[36:37], v[36:37], 1.0 op_sel_hi:[1,0]
	v_pk_add_f32 v[38:39], v[38:39], 1.0 op_sel_hi:[1,0]
	v_pk_add_f32 v[40:41], v[40:41], 1.0 op_sel_hi:[1,0]
	v_rcp_f32_e32 v34, v34
	v_rcp_f32_e32 v35, v35
	v_rcp_f32_e32 v36, v36
	v_rcp_f32_e32 v37, v37
	v_rcp_f32_e32 v38, v38
	v_rcp_f32_e32 v39, v39
	v_rcp_f32_e32 v40, v40
	v_rcp_f32_e32 v41, v41
	v_pk_mul_f32 v[42:43], v[42:43], v[228:229] op_sel_hi:[1,0]
	v_pk_mul_f32 v[44:45], v[44:45], v[228:229] op_sel_hi:[1,0]
	v_pk_mul_f32 v[46:47], v[46:47], v[228:229] op_sel_hi:[1,0]
	v_pk_mul_f32 v[48:49], v[48:49], v[228:229] op_sel_hi:[1,0]
	v_pk_mul_f32 v[42:43], v[42:43], v[34:35]
	v_pk_mul_f32 v[44:45], v[44:45], v[36:37]
	v_pk_mul_f32 v[46:47], v[46:47], v[38:39]
	v_pk_mul_f32 v[48:49], v[48:49], v[40:41]
	v_cvt_pk_bf16_f32 v34, v42, v43
	v_cvt_pk_bf16_f32 v35, v44, v45
	v_cvt_pk_bf16_f32 v36, v46, v47
	v_cvt_pk_bf16_f32 v37, v48, v49
	global_store_dwordx4 v198, v[34:37], s[10:11]
	v_add_u32_e32 v198, 0x16000, v198
	v_mul_f32_e32 v226, 0xbfb8aa3b, v200
	v_mul_f32_e32 v228, v200, v200
	v_pk_mul_f32 v[26:27], v[18:19], v[26:27]
	v_pk_mul_f32 v[28:29], v[20:21], v[28:29]
	v_pk_mul_f32 v[30:31], v[22:23], v[30:31]
	v_pk_mul_f32 v[32:33], v[24:25], v[32:33]
	v_pk_mul_f32 v[18:19], v[18:19], v[226:227] op_sel_hi:[1,0]
	v_pk_mul_f32 v[20:21], v[20:21], v[226:227] op_sel_hi:[1,0]
	v_pk_mul_f32 v[22:23], v[22:23], v[226:227] op_sel_hi:[1,0]
	v_pk_mul_f32 v[24:25], v[24:25], v[226:227] op_sel_hi:[1,0]
	v_exp_f32_e32 v18, v18
	v_exp_f32_e32 v19, v19
	v_exp_f32_e32 v20, v20
	v_exp_f32_e32 v21, v21
	v_exp_f32_e32 v22, v22
	v_exp_f32_e32 v23, v23
	v_exp_f32_e32 v24, v24
	v_exp_f32_e32 v25, v25
	v_pk_add_f32 v[18:19], v[18:19], 1.0 op_sel_hi:[1,0]
	v_pk_add_f32 v[20:21], v[20:21], 1.0 op_sel_hi:[1,0]
	v_pk_add_f32 v[22:23], v[22:23], 1.0 op_sel_hi:[1,0]
	v_pk_add_f32 v[24:25], v[24:25], 1.0 op_sel_hi:[1,0]
	v_rcp_f32_e32 v18, v18
	v_rcp_f32_e32 v19, v19
	v_rcp_f32_e32 v20, v20
	v_rcp_f32_e32 v21, v21
	v_rcp_f32_e32 v22, v22
	v_rcp_f32_e32 v23, v23
	v_rcp_f32_e32 v24, v24
	v_rcp_f32_e32 v25, v25
	v_pk_mul_f32 v[26:27], v[26:27], v[228:229] op_sel_hi:[1,0]
	v_pk_mul_f32 v[28:29], v[28:29], v[228:229] op_sel_hi:[1,0]
	v_pk_mul_f32 v[30:31], v[30:31], v[228:229] op_sel_hi:[1,0]
	v_pk_mul_f32 v[32:33], v[32:33], v[228:229] op_sel_hi:[1,0]
	v_pk_mul_f32 v[26:27], v[26:27], v[18:19]
	v_pk_mul_f32 v[28:29], v[28:29], v[20:21]
	v_pk_mul_f32 v[30:31], v[30:31], v[22:23]
	v_pk_mul_f32 v[32:33], v[32:33], v[24:25]
	v_cvt_pk_bf16_f32 v18, v26, v27
	v_cvt_pk_bf16_f32 v19, v28, v29
	v_cvt_pk_bf16_f32 v20, v30, v31
	v_cvt_pk_bf16_f32 v21, v32, v33
	global_store_dwordx4 v198, v[18:21], s[10:11]
	v_add_u32_e32 v198, 0x16000, v198
	v_mul_f32_e32 v226, 0xbfb8aa3b, v201
	v_mul_f32_e32 v228, v201, v201
	v_pk_mul_f32 v[10:11], v[2:3], v[10:11]
	v_pk_mul_f32 v[12:13], v[4:5], v[12:13]
	v_pk_mul_f32 v[14:15], v[6:7], v[14:15]
	v_pk_mul_f32 v[16:17], v[8:9], v[16:17]
	v_pk_mul_f32 v[2:3], v[2:3], v[226:227] op_sel_hi:[1,0]
	v_pk_mul_f32 v[4:5], v[4:5], v[226:227] op_sel_hi:[1,0]
	v_pk_mul_f32 v[6:7], v[6:7], v[226:227] op_sel_hi:[1,0]
	v_pk_mul_f32 v[8:9], v[8:9], v[226:227] op_sel_hi:[1,0]
	v_exp_f32_e32 v2, v2
	v_exp_f32_e32 v3, v3
	v_exp_f32_e32 v4, v4
	v_exp_f32_e32 v5, v5
	v_exp_f32_e32 v6, v6
	v_exp_f32_e32 v7, v7
	v_exp_f32_e32 v8, v8
	v_exp_f32_e32 v9, v9
	v_pk_add_f32 v[2:3], v[2:3], 1.0 op_sel_hi:[1,0]
	v_pk_add_f32 v[4:5], v[4:5], 1.0 op_sel_hi:[1,0]
	v_pk_add_f32 v[6:7], v[6:7], 1.0 op_sel_hi:[1,0]
	v_pk_add_f32 v[8:9], v[8:9], 1.0 op_sel_hi:[1,0]
	v_rcp_f32_e32 v2, v2
	v_rcp_f32_e32 v3, v3
	v_rcp_f32_e32 v4, v4
	v_rcp_f32_e32 v5, v5
	v_rcp_f32_e32 v6, v6
	v_rcp_f32_e32 v7, v7
	v_rcp_f32_e32 v8, v8
	v_rcp_f32_e32 v9, v9
	v_pk_mul_f32 v[10:11], v[10:11], v[228:229] op_sel_hi:[1,0]
	v_pk_mul_f32 v[12:13], v[12:13], v[228:229] op_sel_hi:[1,0]
	v_pk_mul_f32 v[14:15], v[14:15], v[228:229] op_sel_hi:[1,0]
	v_pk_mul_f32 v[16:17], v[16:17], v[228:229] op_sel_hi:[1,0]
	v_pk_mul_f32 v[10:11], v[10:11], v[2:3]
	v_pk_mul_f32 v[12:13], v[12:13], v[4:5]
	v_pk_mul_f32 v[14:15], v[14:15], v[6:7]
	v_pk_mul_f32 v[16:17], v[16:17], v[8:9]
	v_cvt_pk_bf16_f32 v2, v10, v11
	v_cvt_pk_bf16_f32 v3, v12, v13
	v_cvt_pk_bf16_f32 v4, v14, v15
	v_cvt_pk_bf16_f32 v5, v16, v17
	global_store_dwordx4 v198, v[2:5], s[10:11]
	s_nop 1
	v_mov_b64_e32 v[50:51], 0
	v_mov_b64_e32 v[52:53], 0
	v_mov_b64_e32 v[54:55], 0
	v_mov_b64_e32 v[56:57], 0
	v_mov_b64_e32 v[58:59], 0
	v_mov_b64_e32 v[60:61], 0
	v_mov_b64_e32 v[62:63], 0
	v_mov_b64_e32 v[64:65], 0
	v_mov_b64_e32 v[34:35], 0
	v_mov_b64_e32 v[36:37], 0
	v_mov_b64_e32 v[38:39], 0
	v_mov_b64_e32 v[40:41], 0
	v_mov_b64_e32 v[42:43], 0
	v_mov_b64_e32 v[44:45], 0
	v_mov_b64_e32 v[46:47], 0
	v_mov_b64_e32 v[48:49], 0
	v_mov_b64_e32 v[18:19], 0
	v_mov_b64_e32 v[20:21], 0
	v_mov_b64_e32 v[22:23], 0
	v_mov_b64_e32 v[24:25], 0
	v_mov_b64_e32 v[26:27], 0
	v_mov_b64_e32 v[28:29], 0
	v_mov_b64_e32 v[30:31], 0
	v_mov_b64_e32 v[32:33], 0
	v_mov_b64_e32 v[2:3], 0
	v_mov_b64_e32 v[4:5], 0
	v_mov_b64_e32 v[6:7], 0
	v_mov_b64_e32 v[8:9], 0
	v_mov_b64_e32 v[10:11], 0
	v_mov_b64_e32 v[12:13], 0
	v_mov_b64_e32 v[14:15], 0
	v_mov_b64_e32 v[16:17], 0
	s_mov_b32 s101, 0
	s_waitcnt vmcnt(16)
	s_branch .Ldef_sp2_join

; #define PG8_STAGE(bufoff, gbase, voff) do { _Pragma("unroll") for (int _i = 0; _i < 2; ++_i) \
;         __builtin_amdgcn_global_load_lds((const unsigned*)((const char*)(gbase) + (voff)[_i]), (PG8_LAS unsigned*)(lds + (bufoff) + ldsw + _i * 8192), 16, 0, 0); } while (0)
; #define PG8_LDA(dst, b, h) do { _Pragma("unroll") for (int m = 0; m < 4; ++m) _Pragma("unroll") for (int k = 0; k < 2; ++k) dst[m][k] = *(const PG8_LAS bf16x8*)(lds + PG8_SA(b, h) + aoff + m * 2048 + k * 1024); } while (0)
; #define PG8_LDB(dst, b, h) do { _Pragma("unroll") for (int n = 0; n < 2; ++n) _Pragma("unroll") for (int k = 0; k < 2; ++k) dst[n][k] = *(const PG8_LAS bf16x8*)(lds + PG8_SB(b, h) + boff + n * 2048 + k * 1024); } while (0)
; #define PG8_MMA(ai, bj, At, Bt) do { __builtin_amdgcn_s_setprio(1); _Pragma("unroll") for (int m = 0; m < 4; ++m) _Pragma("unroll") for (int n = 0; n < 2; ++n) _Pragma("unroll") for (int k = 0; k < 2; ++k) \
;         acc[ai][bj][m][n] = __builtin_amdgcn_mfma_f32_16x16x32_bf16(Bt[n][k], At[m][k], acc[ai][bj][m][n], 0, 0, 0); __builtin_amdgcn_s_setprio(0); } while (0)
; #define PG8_WAIT_V(n) asm volatile("s_waitcnt vmcnt(" #n ")" ::: "memory")
; #define PG8_WAIT_L(n) asm volatile("s_waitcnt lgkmcnt(" #n ")" ::: "memory")
; #define PG8_BAR __builtin_amdgcn_s_barrier()
; #define PG8_SCHED __builtin_amdgcn_sched_barrier(0)
; template <class Epi, class Sched, bool ALIGN_EPI = false, bool SP2 = false>
; __device__ __forceinline__ void gemm_phase(PG8_LAS unsigned char* lds, const Gemm g, const Sched& S, const Epi& E) {
;     ...
;             PG8_WAIT_V(8); PG8_WAIT_L(0); PG8_BAR; PG8_MMA(1, 0, At, B0); PG8_MMA(1, 1, At, B1); PG8_BAR; PG8_SCHED;
;             PG8_LDB(B0, 1, 0); PG8_LDB(B1, 1, 1); PG8_SCHED; PG8_LDA(At, 1, 0); PG8_STAGE(PG8_SA(0, 1), a2 + hstep, voffA);
;             PG8_WAIT_V(8); PG8_WAIT_L(0); PG8_BAR; PG8_MMA(0, 0, At, B0); PG8_MMA(0, 1, At, B1); PG8_BAR; PG8_SCHED;
.Ldef_sp2_join:
	s_waitcnt lgkmcnt(0)
	s_barrier
	s_setprio 1
	v_mfma_f32_16x16x32_bf16 v[50:53], v[146:149], v[178:181], v[50:53]
	v_mfma_f32_16x16x32_bf16 v[50:53], v[150:153], v[182:185], v[50:53]
	v_mfma_f32_16x16x32_bf16 v[34:37], v[146:149], v[186:189], v[34:37]
	v_mfma_f32_16x16x32_bf16 v[34:37], v[150:153], v[190:193], v[34:37]
	v_mfma_f32_16x16x32_bf16 v[18:21], v[146:149], v[202:205], v[18:21]
	v_mfma_f32_16x16x32_bf16 v[18:21], v[150:153], v[206:209], v[18:21]
	v_mfma_f32_16x16x32_bf16 v[2:5], v[146:149], v[210:213], v[2:5]
	v_mfma_f32_16x16x32_bf16 v[2:5], v[150:153], v[214:217], v[2:5]
	v_mfma_f32_16x16x32_bf16 v[54:57], v[154:157], v[178:181], v[54:57]
	v_mfma_f32_16x16x32_bf16 v[54:57], v[158:161], v[182:185], v[54:57]
	v_mfma_f32_16x16x32_bf16 v[38:41], v[154:157], v[186:189], v[38:41]
	v_mfma_f32_16x16x32_bf16 v[38:41], v[158:161], v[190:193], v[38:41]
	v_mfma_f32_16x16x32_bf16 v[22:25], v[154:157], v[202:205], v[22:25]
	v_mfma_f32_16x16x32_bf16 v[22:25], v[158:161], v[206:209], v[22:25]
	v_mfma_f32_16x16x32_bf16 v[6:9], v[154:157], v[210:213], v[6:9]
	v_mfma_f32_16x16x32_bf16 v[6:9], v[158:161], v[214:217], v[6:9]
	v_mfma_f32_16x16x32_bf16 v[58:61], v[162:165], v[178:181], v[58:61]
	v_mfma_f32_16x16x32_bf16 v[58:61], v[166:169], v[182:185], v[58:61]
	v_mfma_f32_16x16x32_bf16 v[42:45], v[162:165], v[186:189], v[42:45]
	v_mfma_f32_16x16x32_bf16 v[42:45], v[166:169], v[190:193], v[42:45]
	v_mfma_f32_16x16x32_bf16 v[26:29], v[162:165], v[202:205], v[26:29]
	v_mfma_f32_16x16x32_bf16 v[26:29], v[166:169], v[206:209], v[26:29]
	v_mfma_f32_16x16x32_bf16 v[10:13], v[162:165], v[210:213], v[10:13]
	v_mfma_f32_16x16x32_bf16 v[10:13], v[166:169], v[214:217], v[10:13]
	v_mfma_f32_16x16x32_bf16 v[62:65], v[170:173], v[178:181], v[62:65]
	v_mfma_f32_16x16x32_bf16 v[62:65], v[174:177], v[182:185], v[62:65]
	v_mfma_f32_16x16x32_bf16 v[46:49], v[170:173], v[186:189], v[46:49]
	v_mfma_f32_16x16x32_bf16 v[46:49], v[174:177], v[190:193], v[46:49]
	v_mfma_f32_16x16x32_bf16 v[30:33], v[170:173], v[202:205], v[30:33]
	v_mfma_f32_16x16x32_bf16 v[30:33], v[174:177], v[206:209], v[30:33]
	v_mfma_f32_16x16x32_bf16 v[14:17], v[170:173], v[210:213], v[14:17]
	v_mfma_f32_16x16x32_bf16 v[14:17], v[174:177], v[214:217], v[14:17]
	s_setprio 0
	s_barrier
	s_add_i32 s18, 0, 0x18000
	v_add_u32_e32 v145, s18, v141
	s_add_i32 s83, 0, 0x1c000
	ds_read_b128 v[146:149], v145
	ds_read_b128 v[150:153], v145 offset:1024
	ds_read_b128 v[154:157], v145 offset:2048
	ds_read_b128 v[158:161], v145 offset:3072
	v_add_u32_e32 v145, s83, v141
	ds_read_b128 v[162:165], v145
	ds_read_b128 v[166:169], v145 offset:1024
	ds_read_b128 v[170:173], v145 offset:2048
	ds_read_b128 v[174:177], v145 offset:3072
	s_add_u32 s38, s64, 0x40000
	s_addc_u32 s39, s65, 0
	s_mov_b32 m0, s58
	v_lshl_add_u64 v[224:225], s[38:39], 0, v[134:135]
	ds_read_b128 v[178:181], v144 offset:32768
	ds_read_b128 v[182:185], v144 offset:33792
	ds_read_b128 v[186:189], v144 offset:34816
	ds_read_b128 v[190:193], v144 offset:35840
	ds_read_b128 v[202:205], v144 offset:36864
	ds_read_b128 v[206:209], v144 offset:37888
	ds_read_b128 v[210:213], v144 offset:38912
	ds_read_b128 v[214:217], v144 offset:39936
	global_load_lds_dwordx4 v[224:225], off
	v_lshl_add_u64 v[224:225], s[38:39], 0, v[132:133]
	s_mov_b32 m0, s69
	s_nop 0
	global_load_lds_dwordx4 v[224:225], off
	s_waitcnt vmcnt(8)
	s_waitcnt lgkmcnt(0)
	s_barrier
	s_setprio 1
	v_mfma_f32_16x16x32_bf16 v[114:117], v[146:149], v[178:181], v[114:117]
	v_mfma_f32_16x16x32_bf16 v[114:117], v[150:153], v[182:185], v[114:117]
	v_mfma_f32_16x16x32_bf16 v[98:101], v[146:149], v[186:189], v[98:101]
	v_mfma_f32_16x16x32_bf16 v[98:101], v[150:153], v[190:193], v[98:101]
	v_mfma_f32_16x16x32_bf16 v[82:85], v[146:149], v[202:205], v[82:85]
	v_mfma_f32_16x16x32_bf16 v[82:85], v[150:153], v[206:209], v[82:85]
	v_mfma_f32_16x16x32_bf16 v[66:69], v[146:149], v[210:213], v[66:69]
	v_mfma_f32_16x16x32_bf16 v[66:69], v[150:153], v[214:217], v[66:69]
	v_mfma_f32_16x16x32_bf16 v[118:121], v[154:157], v[178:181], v[118:121]
	v_mfma_f32_16x16x32_bf16 v[118:121], v[158:161], v[182:185], v[118:121]
	v_mfma_f32_16x16x32_bf16 v[102:105], v[154:157], v[186:189], v[102:105]
	v_mfma_f32_16x16x32_bf16 v[102:105], v[158:161], v[190:193], v[102:105]
	v_mfma_f32_16x16x32_bf16 v[86:89], v[154:157], v[202:205], v[86:89]
	v_mfma_f32_16x16x32_bf16 v[86:89], v[158:161], v[206:209], v[86:89]
	v_mfma_f32_16x16x32_bf16 v[70:73], v[154:157], v[210:213], v[70:73]
	v_mfma_f32_16x16x32_bf16 v[70:73], v[158:161], v[214:217], v[70:73]
	v_mfma_f32_16x16x32_bf16 v[122:125], v[162:165], v[178:181], v[122:125]
	v_mfma_f32_16x16x32_bf16 v[122:125], v[166:169], v[182:185], v[122:125]
	v_mfma_f32_16x16x32_bf16 v[106:109], v[162:165], v[186:189], v[106:109]
	v_mfma_f32_16x16x32_bf16 v[106:109], v[166:169], v[190:193], v[106:109]
	v_mfma_f32_16x16x32_bf16 v[90:93], v[162:165], v[202:205], v[90:93]
	v_mfma_f32_16x16x32_bf16 v[90:93], v[166:169], v[206:209], v[90:93]
	v_mfma_f32_16x16x32_bf16 v[74:77], v[162:165], v[210:213], v[74:77]
	v_mfma_f32_16x16x32_bf16 v[74:77], v[166:169], v[214:217], v[74:77]
	v_mfma_f32_16x16x32_bf16 v[126:129], v[170:173], v[178:181], v[126:129]
	v_mfma_f32_16x16x32_bf16 v[126:129], v[174:177], v[182:185], v[126:129]
	v_mfma_f32_16x16x32_bf16 v[110:113], v[170:173], v[186:189], v[110:113]
	v_mfma_f32_16x16x32_bf16 v[110:113], v[174:177], v[190:193], v[110:113]
	v_mfma_f32_16x16x32_bf16 v[94:97], v[170:173], v[202:205], v[94:97]
	v_mfma_f32_16x16x32_bf16 v[94:97], v[174:177], v[206:209], v[94:97]
	v_mfma_f32_16x16x32_bf16 v[78:81], v[170:173], v[210:213], v[78:81]
	v_mfma_f32_16x16x32_bf16 v[78:81], v[174:177], v[214:217], v[78:81]
	s_setprio 0
	s_barrier
; #define PG8_STAGE(bufoff, gbase, voff) do { _Pragma("unroll") for (int _i = 0; _i < 2; ++_i) \
;         __builtin_amdgcn_global_load_lds((const unsigned*)((const char*)(gbase) + (voff)[_i]), (PG8_LAS unsigned*)(lds + (bufoff) + ldsw + _i * 8192), 16, 0, 0); } while (0)
; #define PG8_LDA(dst, b, h) do { _Pragma("unroll") for (int m = 0; m < 4; ++m) _Pragma("unroll") for (int k = 0; k < 2; ++k) dst[m][k] = *(const PG8_LAS bf16x8*)(lds + PG8_SA(b, h) + aoff + m * 2048 + k * 1024); } while (0)
; #define PG8_MMA(ai, bj, At, Bt) do { __builtin_amdgcn_s_setprio(1); _Pragma("unroll") for (int m = 0; m < 4; ++m) _Pragma("unroll") for (int n = 0; n < 2; ++n) _Pragma("unroll") for (int k = 0; k < 2; ++k) \
;         acc[ai][bj][m][n] = __builtin_amdgcn_mfma_f32_16x16x32_bf16(Bt[n][k], At[m][k], acc[ai][bj][m][n], 0, 0, 0); __builtin_amdgcn_s_setprio(0); } while (0)
; #define PG8_WAIT_V(n) asm volatile("s_waitcnt vmcnt(" #n ")" ::: "memory")
; #define PG8_WAIT_L(n) asm volatile("s_waitcnt lgkmcnt(" #n ")" ::: "memory")
; #define PG8_BAR __builtin_amdgcn_s_barrier()
; #define PG8_SCHED __builtin_amdgcn_sched_barrier(0)
; template <class Epi, class Sched, bool ALIGN_EPI = false, bool SP2 = false>
; __device__ __forceinline__ void gemm_phase(PG8_LAS unsigned char* lds, const Gemm g, const Sched& S, const Epi& E) {
;     ...
;             PG8_LDA(At, 1, 1); PG8_STAGE(PG8_SB(1, 0), b3, voffB); PG8_STAGE(PG8_SB(1, 1), b3 + hstep, voffB); PG8_STAGE(PG8_SA(1, 0), a3, voffA);
;             PG8_WAIT_V(8); PG8_WAIT_L(0); PG8_BAR; PG8_MMA(1, 0, At, B0); PG8_MMA(1, 1, At, B1); PG8_BAR; PG8_SCHED;
;     ...
;         if constexpr (ALIGN_EPI) { if (wr == 0) PG8_BAR; }
;         if constexpr (!Epi::AFTER_DRAIN) { E(acc, cur, wr, wc, fr, fq, lds, rs_pm, rs_tog); S.done(cur); }
;         if (!has_next) break;
	s_add_i32 s18, s18, s27
	v_lshl_add_u64 v[194:195], v[194:195], 0, s[30:31]
	s_mov_b32 m0, s18
	ds_read_b128 v[178:181], v144 offset:49152
	ds_read_b128 v[182:185], v144 offset:50176
	ds_read_b128 v[186:189], v144 offset:51200
	ds_read_b128 v[190:193], v144 offset:52224
	ds_read_b128 v[202:205], v144 offset:53248
	ds_read_b128 v[206:209], v144 offset:54272
	ds_read_b128 v[210:213], v144 offset:55296
	ds_read_b128 v[214:217], v144 offset:56320
	global_load_lds_dwordx4 v[194:195], off
	s_add_i32 m0, s18, 0x2000
	s_add_u32 s38, s56, 0x40080
	v_lshl_add_u64 v[194:195], v[218:219], 0, s[30:31]
	s_addc_u32 s39, s57, 0
	s_add_i32 s18, s83, s27
	global_load_lds_dwordx4 v[194:195], off
	v_lshl_add_u64 v[194:195], s[38:39], 0, v[0:1]
	s_mov_b32 m0, s18
	s_nop 0
	global_load_lds_dwordx4 v[194:195], off
	v_lshl_add_u64 v[194:195], s[38:39], 0, v[130:131]
	s_add_i32 m0, s18, 0x2000
	s_nop 0
	global_load_lds_dwordx4 v[194:195], off
	v_lshl_add_u64 v[194:195], v[220:221], 0, s[30:31]
	s_mov_b32 m0, s71
	s_nop 0
	global_load_lds_dwordx4 v[194:195], off
	v_lshl_add_u64 v[194:195], v[222:223], 0, s[30:31]
	s_mov_b32 m0, s72
	s_nop 0
	global_load_lds_dwordx4 v[194:195], off
	s_waitcnt vmcnt(8)
	s_waitcnt lgkmcnt(0)
	s_barrier
	s_setprio 1
	v_mfma_f32_16x16x32_bf16 v[50:53], v[146:149], v[178:181], v[50:53]
	v_mfma_f32_16x16x32_bf16 v[50:53], v[150:153], v[182:185], v[50:53]
	v_mfma_f32_16x16x32_bf16 v[34:37], v[146:149], v[186:189], v[34:37]
	v_mfma_f32_16x16x32_bf16 v[34:37], v[150:153], v[190:193], v[34:37]
	v_mfma_f32_16x16x32_bf16 v[18:21], v[146:149], v[202:205], v[18:21]
	v_mfma_f32_16x16x32_bf16 v[18:21], v[150:153], v[206:209], v[18:21]
	v_mfma_f32_16x16x32_bf16 v[2:5], v[146:149], v[210:213], v[2:5]
	v_mfma_f32_16x16x32_bf16 v[2:5], v[150:153], v[214:217], v[2:5]
	v_mfma_f32_16x16x32_bf16 v[54:57], v[154:157], v[178:181], v[54:57]
	v_mfma_f32_16x16x32_bf16 v[54:57], v[158:161], v[182:185], v[54:57]
	v_mfma_f32_16x16x32_bf16 v[38:41], v[154:157], v[186:189], v[38:41]
	v_mfma_f32_16x16x32_bf16 v[38:41], v[158:161], v[190:193], v[38:41]
	v_mfma_f32_16x16x32_bf16 v[22:25], v[154:157], v[202:205], v[22:25]
	v_mfma_f32_16x16x32_bf16 v[22:25], v[158:161], v[206:209], v[22:25]
	v_mfma_f32_16x16x32_bf16 v[6:9], v[154:157], v[210:213], v[6:9]
	v_mfma_f32_16x16x32_bf16 v[6:9], v[158:161], v[214:217], v[6:9]
	v_mfma_f32_16x16x32_bf16 v[58:61], v[162:165], v[178:181], v[58:61]
	v_mfma_f32_16x16x32_bf16 v[58:61], v[166:169], v[182:185], v[58:61]
	v_mfma_f32_16x16x32_bf16 v[42:45], v[162:165], v[186:189], v[42:45]
	v_mfma_f32_16x16x32_bf16 v[42:45], v[166:169], v[190:193], v[42:45]
	v_mfma_f32_16x16x32_bf16 v[26:29], v[162:165], v[202:205], v[26:29]
	v_mfma_f32_16x16x32_bf16 v[26:29], v[166:169], v[206:209], v[26:29]
	v_mfma_f32_16x16x32_bf16 v[10:13], v[162:165], v[210:213], v[10:13]
	v_mfma_f32_16x16x32_bf16 v[10:13], v[166:169], v[214:217], v[10:13]
	v_mfma_f32_16x16x32_bf16 v[62:65], v[170:173], v[178:181], v[62:65]
	v_mfma_f32_16x16x32_bf16 v[62:65], v[174:177], v[182:185], v[62:65]
	v_mfma_f32_16x16x32_bf16 v[46:49], v[170:173], v[186:189], v[46:49]
	v_mfma_f32_16x16x32_bf16 v[46:49], v[174:177], v[190:193], v[46:49]
	v_mfma_f32_16x16x32_bf16 v[30:33], v[170:173], v[202:205], v[30:33]
	v_mfma_f32_16x16x32_bf16 v[30:33], v[174:177], v[206:209], v[30:33]
	v_mfma_f32_16x16x32_bf16 v[14:17], v[170:173], v[210:213], v[14:17]
	v_mfma_f32_16x16x32_bf16 v[14:17], v[174:177], v[214:217], v[14:17]
	s_setprio 0
	s_barrier
	s_add_i32 s82, s82, 2
	s_add_u32 s60, s60, 0x100
	s_addc_u32 s61, s61, 0
	s_add_u32 s80, s80, 0x100
	s_addc_u32 s81, s81, 0
	s_cmp_gt_u32 s82, 13
	s_cbranch_scc0 .LBB0_220
	s_cmp_lg_u32 s77, s75
	s_cbranch_scc1 .Ldef_no
	s_and_b64 vcc, exec, s[42:43]
	s_cbranch_vccz .Ldef_no
	s_mov_b32 s100, s76
	s_mov_b32 s101, 1
	s_branch .LBB0_215
